# attention P*V: V fragments read with ds_read_b64 straight into MFMA operand registers (48 v_mov per key tile removed), on top of v124
# speedup vs baseline: 1.0143x; 1.0105x over previous
.LBB0_517:
	v_mov_b32_e32 v220, 0x3e38aa3b
	v_mul_f32_e32 v222, 0xbe38aa3b, v163
	v_mul_f32_e32 v224, 0xbe38aa3b, v3
	v_pk_fma_f32 v[100:101], v[100:101], v[220:221], v[222:223] op_sel_hi:[1,0,0]
	v_pk_fma_f32 v[102:103], v[102:103], v[220:221], v[222:223] op_sel_hi:[1,0,0]
	v_pk_fma_f32 v[104:105], v[104:105], v[220:221], v[222:223] op_sel_hi:[1,0,0]
	v_pk_fma_f32 v[106:107], v[106:107], v[220:221], v[222:223] op_sel_hi:[1,0,0]
	v_pk_fma_f32 v[108:109], v[108:109], v[220:221], v[222:223] op_sel_hi:[1,0,0]
	v_pk_fma_f32 v[110:111], v[110:111], v[220:221], v[222:223] op_sel_hi:[1,0,0]
	v_pk_fma_f32 v[112:113], v[112:113], v[220:221], v[222:223] op_sel_hi:[1,0,0]
	v_pk_fma_f32 v[114:115], v[114:115], v[220:221], v[222:223] op_sel_hi:[1,0,0]
	v_pk_fma_f32 v[84:85], v[84:85], v[220:221], v[224:225] op_sel_hi:[1,0,0]
	v_pk_fma_f32 v[86:87], v[86:87], v[220:221], v[224:225] op_sel_hi:[1,0,0]
	v_pk_fma_f32 v[88:89], v[88:89], v[220:221], v[224:225] op_sel_hi:[1,0,0]
	v_pk_fma_f32 v[90:91], v[90:91], v[220:221], v[224:225] op_sel_hi:[1,0,0]
	v_pk_fma_f32 v[92:93], v[92:93], v[220:221], v[224:225] op_sel_hi:[1,0,0]
	v_pk_fma_f32 v[94:95], v[94:95], v[220:221], v[224:225] op_sel_hi:[1,0,0]
	v_pk_fma_f32 v[96:97], v[96:97], v[220:221], v[224:225] op_sel_hi:[1,0,0]
	v_pk_fma_f32 v[98:99], v[98:99], v[220:221], v[224:225] op_sel_hi:[1,0,0]
	v_exp_f32_e32 v104, v104
	v_exp_f32_e32 v167, v84
	v_exp_f32_e32 v105, v105
	v_exp_f32_e32 v106, v106
	v_exp_f32_e32 v168, v85
	v_exp_f32_e32 v107, v107
	v_add_f32_e32 v175, 0, v104
	v_exp_f32_e32 v176, v100
	v_exp_f32_e32 v169, v86
	v_add_f32_e32 v175, v105, v175
	v_exp_f32_e32 v101, v101
	v_add_f32_e32 v175, v106, v175
	v_exp_f32_e32 v102, v102
	v_exp_f32_e32 v170, v87
	v_add_f32_e32 v175, v107, v175
	v_exp_f32_e32 v103, v103
	v_add_f32_e32 v100, v176, v175
	v_exp_f32_e32 v108, v108
	v_exp_f32_e32 v88, v88
	v_add_f32_e32 v100, v101, v100
	v_exp_f32_e32 v109, v109
	v_add_f32_e32 v100, v102, v100
	v_exp_f32_e32 v110, v110
	v_exp_f32_e32 v89, v89
	v_add_f32_e32 v100, v103, v100
	v_exp_f32_e32 v111, v111
	v_add_f32_e32 v100, v108, v100
	v_exp_f32_e32 v112, v112
	v_exp_f32_e32 v90, v90
	v_add_f32_e32 v100, v109, v100
	v_exp_f32_e32 v113, v113
	v_add_f32_e32 v100, v110, v100
	v_exp_f32_e32 v114, v114
	v_exp_f32_e32 v91, v91
	v_add_f32_e32 v100, v111, v100
	v_exp_f32_e32 v115, v115
	v_add_f32_e32 v100, v112, v100
	v_exp_f32_e32 v171, v92
	v_add_f32_e32 v100, v113, v100
	v_add_f32_e32 v100, v114, v100
	v_exp_f32_e32 v172, v93
	v_add_f32_e32 v100, v115, v100
	v_fmac_f32_e32 v100, v166, v2
	v_add_f32_e32 v2, 0, v167
	v_exp_f32_e32 v173, v94
	v_add_f32_e32 v2, v168, v2
	v_add_f32_e32 v2, v169, v2
	v_exp_f32_e32 v174, v95
	v_add_f32_e32 v2, v170, v2
	v_add_f32_e32 v2, v88, v2
	v_exp_f32_e32 v96, v96
	v_add_f32_e32 v2, v89, v2
	v_add_f32_e32 v2, v90, v2
	v_exp_f32_e32 v97, v97
	v_add_f32_e32 v2, v91, v2
	v_add_f32_e32 v2, v171, v2
	v_exp_f32_e32 v98, v98
	v_add_f32_e32 v2, v172, v2
	v_add_f32_e32 v2, v173, v2
	v_exp_f32_e32 v99, v99
	v_add_f32_e32 v2, v174, v2
	v_add_f32_e32 v2, v96, v2
	v_add_f32_e32 v2, v97, v2
	v_add_f32_e32 v2, v98, v2
	v_add_f32_e32 v2, v99, v2
	v_fmac_f32_e32 v2, v165, v0
	v_add3_u32 v0, v164, v153, v152
	v_cvt_pk_bf16_f32 v95, v90, v91
	v_cvt_pk_bf16_f32 v87, v98, v99
	v_cvt_pk_bf16_f32 v98, v176, v101
	v_cvt_pk_bf16_f32 v91, v114, v115
	v_add_u32_e32 v101, v0, v158
	v_add_u32_e32 v114, v0, v160
	v_cvt_pk_bf16_f32 v94, v88, v89
	v_cvt_pk_bf16_f32 v86, v96, v97
	v_cvt_pk_bf16_f32 v96, v104, v105
	v_cvt_pk_bf16_f32 v97, v106, v107
	v_cvt_pk_bf16_f32 v99, v102, v103
	v_cvt_pk_bf16_f32 v88, v108, v109
	ds_read_b64 v[106:107], v101 offset:18432
	ds_read_b64 v[108:109], v114 offset:18432
	v_cvt_pk_bf16_f32 v90, v112, v113
	ds_read_b64 v[112:113], v114 offset:16384
	v_cvt_pk_bf16_f32 v92, v167, v168
	v_cvt_pk_bf16_f32 v93, v169, v170
	v_cvt_pk_bf16_f32 v89, v110, v111
	ds_read_b64 v[110:111], v101 offset:16384
	s_waitcnt lgkmcnt(0)
	v_mfma_f32_16x16x32_bf16 v[72:75], v[106:109], v[92:95], v[72:75]
	v_cvt_pk_bf16_f32 v84, v171, v172
	v_cvt_pk_bf16_f32 v85, v173, v174
	s_add_i32 s1, s1, 1
	v_mfma_f32_16x16x32_bf16 v[68:71], v[106:109], v[96:99], v[68:71]
	ds_read_b64 v[106:107], v101 offset:22528
	ds_read_b64 v[108:109], v114 offset:22528
	s_add_i32 s0, s0, 0x8000
	v_lshl_add_u64 v[122:123], v[122:123], 0, s[70:71]
	v_mfma_f32_16x16x32_bf16 v[80:83], v[110:113], v[92:95], v[80:83]
	v_lshl_add_u64 v[124:125], v[124:125], 0, s[70:71]
	v_lshl_add_u64 v[126:127], v[126:127], 0, s[70:71]
	v_lshl_add_u64 v[128:129], v[128:129], 0, s[70:71]
	v_mfma_f32_16x16x32_bf16 v[76:79], v[110:113], v[96:99], v[76:79]
	ds_read_b64 v[110:111], v101 offset:20480
	ds_read_b64 v[112:113], v114 offset:20480
	s_waitcnt lgkmcnt(0)
	v_mfma_f32_16x16x32_bf16 v[56:59], v[106:109], v[92:95], v[56:59]
	v_lshl_add_u64 v[132:133], v[132:133], 0, s[64:65]
	v_lshl_add_u64 v[134:135], v[134:135], 0, s[64:65]
	v_lshl_add_u64 v[136:137], v[136:137], 0, s[64:65]
	v_mfma_f32_16x16x32_bf16 v[52:55], v[106:109], v[96:99], v[52:55]
	ds_read_b64 v[106:107], v101 offset:26624
	ds_read_b64 v[108:109], v114 offset:26624
	v_lshl_add_u64 v[138:139], v[138:139], 0, s[64:65]
	s_cmp_lg_u32 s1, 4
	v_mfma_f32_16x16x32_bf16 v[64:67], v[110:113], v[92:95], v[64:67]
	v_mfma_f32_16x16x32_bf16 v[60:63], v[110:113], v[96:99], v[60:63]
	ds_read_b64 v[110:111], v101 offset:24576
	ds_read_b64 v[112:113], v114 offset:24576
	s_waitcnt lgkmcnt(0)
	v_mfma_f32_16x16x32_bf16 v[40:43], v[106:109], v[92:95], v[40:43]
	v_mfma_f32_16x16x32_bf16 v[36:39], v[106:109], v[96:99], v[36:39]
	ds_read_b64 v[106:107], v101 offset:30720
	ds_read_b64 v[108:109], v114 offset:30720
	v_add_u32_e32 v226, v0, v161
	v_mfma_f32_16x16x32_bf16 v[48:51], v[110:113], v[92:95], v[48:51]
	v_add_u32_e32 v228, v0, v162
	v_mfma_f32_16x16x32_bf16 v[44:47], v[110:113], v[96:99], v[44:47]
	ds_read_b64 v[110:111], v101 offset:28672
	ds_read_b64 v[112:113], v114 offset:28672
	s_waitcnt lgkmcnt(0)
	v_mfma_f32_16x16x32_bf16 v[32:35], v[110:113], v[92:95], v[32:35]
	v_mfma_f32_16x16x32_bf16 v[20:23], v[110:113], v[96:99], v[20:23]
	v_mfma_f32_16x16x32_bf16 v[24:27], v[106:109], v[92:95], v[24:27]
	ds_read_b64 v[102:103], v226 offset:16384
	s_waitcnt lgkmcnt(0)
	v_mfma_f32_16x16x32_bf16 v[28:31], v[106:109], v[96:99], v[28:31]
	ds_read_b64 v[96:97], v226 offset:18432
	ds_read_b64 v[104:105], v228 offset:16384
	ds_read_b64 v[98:99], v228 offset:18432
	s_waitcnt lgkmcnt(0)
	v_mfma_f32_16x16x32_bf16 v[80:83], v[102:105], v[84:87], v[80:83]
	s_nop 0
	v_mfma_f32_16x16x32_bf16 v[72:75], v[96:99], v[84:87], v[72:75]
	v_mfma_f32_16x16x32_bf16 v[68:71], v[96:99], v[88:91], v[68:71]
	ds_read_b64 v[96:97], v226 offset:22528
	ds_read_b64 v[98:99], v228 offset:22528
	v_mfma_f32_16x16x32_bf16 v[76:79], v[102:105], v[88:91], v[76:79]
	ds_read_b64 v[102:103], v226 offset:20480
	ds_read_b64 v[104:105], v228 offset:20480
	s_waitcnt lgkmcnt(0)
	s_nop 0
	v_mfma_f32_16x16x32_bf16 v[56:59], v[96:99], v[84:87], v[56:59]
	v_mfma_f32_16x16x32_bf16 v[52:55], v[96:99], v[88:91], v[52:55]
	ds_read_b64 v[96:97], v226 offset:26624
	ds_read_b64 v[98:99], v228 offset:26624
	v_mfma_f32_16x16x32_bf16 v[64:67], v[102:105], v[84:87], v[64:67]
	v_mfma_f32_16x16x32_bf16 v[60:63], v[102:105], v[88:91], v[60:63]
	ds_read_b64 v[102:103], v226 offset:24576
	ds_read_b64 v[104:105], v228 offset:24576
	s_waitcnt lgkmcnt(0)
	v_mfma_f32_16x16x32_bf16 v[40:43], v[96:99], v[84:87], v[40:43]
	v_mfma_f32_16x16x32_bf16 v[36:39], v[96:99], v[88:91], v[36:39]
	ds_read_b64 v[96:97], v226 offset:30720
	ds_read_b64 v[98:99], v228 offset:30720
	v_mfma_f32_16x16x32_bf16 v[48:51], v[102:105], v[84:87], v[48:51]
	v_mfma_f32_16x16x32_bf16 v[44:47], v[102:105], v[88:91], v[44:47]
	ds_read_b64 v[102:103], v226 offset:28672
	ds_read_b64 v[104:105], v228 offset:28672
	s_waitcnt lgkmcnt(0)
	v_mfma_f32_16x16x32_bf16 v[32:35], v[102:105], v[84:87], v[32:35]
	v_mfma_f32_16x16x32_bf16 v[20:23], v[102:105], v[88:91], v[20:23]
	v_mfma_f32_16x16x32_bf16 v[24:27], v[96:99], v[84:87], v[24:27]
	v_mfma_f32_16x16x32_bf16 v[28:31], v[96:99], v[88:91], v[28:31]
	s_cbranch_scc0 .LBB0_519
	v_mov_b32_e32 v165, v2
	v_mov_b32_e32 v166, v100
	v_mov_b32_e32 v100, v3
	v_mov_b32_e32 v2, v163
	s_branch .LBB0_511

.LBB0_623:
	v_mov_b32_e32 v220, 0x3e38aa3b
	v_mul_f32_e32 v222, 0xbe38aa3b, v133
	v_mul_f32_e32 v224, 0xbe38aa3b, v3
	v_pk_fma_f32 v[100:101], v[100:101], v[220:221], v[222:223] op_sel_hi:[1,0,0]
	v_pk_fma_f32 v[102:103], v[102:103], v[220:221], v[222:223] op_sel_hi:[1,0,0]
	v_pk_fma_f32 v[104:105], v[104:105], v[220:221], v[222:223] op_sel_hi:[1,0,0]
	v_pk_fma_f32 v[106:107], v[106:107], v[220:221], v[222:223] op_sel_hi:[1,0,0]
	v_pk_fma_f32 v[108:109], v[108:109], v[220:221], v[222:223] op_sel_hi:[1,0,0]
	v_pk_fma_f32 v[110:111], v[110:111], v[220:221], v[222:223] op_sel_hi:[1,0,0]
	v_pk_fma_f32 v[112:113], v[112:113], v[220:221], v[222:223] op_sel_hi:[1,0,0]
	v_pk_fma_f32 v[114:115], v[114:115], v[220:221], v[222:223] op_sel_hi:[1,0,0]
	v_pk_fma_f32 v[84:85], v[84:85], v[220:221], v[224:225] op_sel_hi:[1,0,0]
	v_pk_fma_f32 v[86:87], v[86:87], v[220:221], v[224:225] op_sel_hi:[1,0,0]
	v_pk_fma_f32 v[88:89], v[88:89], v[220:221], v[224:225] op_sel_hi:[1,0,0]
	v_pk_fma_f32 v[90:91], v[90:91], v[220:221], v[224:225] op_sel_hi:[1,0,0]
	v_pk_fma_f32 v[92:93], v[92:93], v[220:221], v[224:225] op_sel_hi:[1,0,0]
	v_pk_fma_f32 v[94:95], v[94:95], v[220:221], v[224:225] op_sel_hi:[1,0,0]
	v_pk_fma_f32 v[96:97], v[96:97], v[220:221], v[224:225] op_sel_hi:[1,0,0]
	v_pk_fma_f32 v[98:99], v[98:99], v[220:221], v[224:225] op_sel_hi:[1,0,0]
	v_exp_f32_e32 v104, v104
	v_exp_f32_e32 v137, v84
	v_exp_f32_e32 v105, v105
	v_exp_f32_e32 v106, v106
	v_exp_f32_e32 v139, v85
	v_exp_f32_e32 v107, v107
	v_add_f32_e32 v182, 0, v104
	v_exp_f32_e32 v183, v100
	v_exp_f32_e32 v141, v86
	v_add_f32_e32 v182, v105, v182
	v_exp_f32_e32 v101, v101
	v_add_f32_e32 v182, v106, v182
	v_exp_f32_e32 v102, v102
	v_exp_f32_e32 v143, v87
	v_add_f32_e32 v182, v107, v182
	v_exp_f32_e32 v103, v103
	v_add_f32_e32 v100, v183, v182
	v_exp_f32_e32 v108, v108
	v_exp_f32_e32 v88, v88
	v_add_f32_e32 v100, v101, v100
	v_exp_f32_e32 v109, v109
	v_add_f32_e32 v100, v102, v100
	v_exp_f32_e32 v110, v110
	v_exp_f32_e32 v89, v89
	v_add_f32_e32 v100, v103, v100
	v_exp_f32_e32 v111, v111
	v_add_f32_e32 v100, v108, v100
	v_exp_f32_e32 v112, v112
	v_exp_f32_e32 v90, v90
	v_add_f32_e32 v100, v109, v100
	v_exp_f32_e32 v113, v113
	v_add_f32_e32 v100, v110, v100
	v_exp_f32_e32 v114, v114
	v_exp_f32_e32 v91, v91
	v_add_f32_e32 v100, v111, v100
	v_exp_f32_e32 v115, v115
	v_add_f32_e32 v100, v112, v100
	v_exp_f32_e32 v145, v92
	v_add_f32_e32 v100, v113, v100
	v_add_f32_e32 v100, v114, v100
	v_exp_f32_e32 v147, v93
	v_add_f32_e32 v100, v115, v100
	v_fmac_f32_e32 v100, v179, v2
	v_add_f32_e32 v2, 0, v137
	v_exp_f32_e32 v180, v94
	v_add_f32_e32 v2, v139, v2
	v_add_f32_e32 v2, v141, v2
	v_exp_f32_e32 v181, v95
	v_add_f32_e32 v2, v143, v2
	v_add_f32_e32 v2, v88, v2
	v_exp_f32_e32 v96, v96
	v_add_f32_e32 v2, v89, v2
	v_add_f32_e32 v2, v90, v2
	v_exp_f32_e32 v97, v97
	v_add_f32_e32 v2, v91, v2
	v_add_f32_e32 v2, v145, v2
	v_exp_f32_e32 v98, v98
	v_add_f32_e32 v2, v147, v2
	v_add_f32_e32 v2, v180, v2
	v_exp_f32_e32 v99, v99
	v_add_f32_e32 v2, v181, v2
	v_add_f32_e32 v2, v96, v2
	v_add_f32_e32 v2, v97, v2
	v_add_f32_e32 v2, v98, v2
	v_add_f32_e32 v2, v99, v2
	v_fmac_f32_e32 v2, v178, v0
	v_add3_u32 v0, v135, v169, v168
	v_cvt_pk_bf16_f32 v95, v90, v91
	v_cvt_pk_bf16_f32 v87, v98, v99
	v_cvt_pk_bf16_f32 v98, v183, v101
	v_cvt_pk_bf16_f32 v91, v114, v115
	v_add_u32_e32 v101, v0, v174
	v_add_u32_e32 v114, v0, v175
	v_cvt_pk_bf16_f32 v94, v88, v89
	v_cvt_pk_bf16_f32 v86, v96, v97
	v_cvt_pk_bf16_f32 v96, v104, v105
	v_cvt_pk_bf16_f32 v97, v106, v107
	v_cvt_pk_bf16_f32 v99, v102, v103
	v_cvt_pk_bf16_f32 v88, v108, v109
	ds_read_b64 v[106:107], v101 offset:18432
	ds_read_b64 v[108:109], v114 offset:18432
	v_cvt_pk_bf16_f32 v90, v112, v113
	ds_read_b64 v[112:113], v114 offset:16384
	v_cvt_pk_bf16_f32 v92, v137, v139
	v_cvt_pk_bf16_f32 v93, v141, v143
	v_cvt_pk_bf16_f32 v89, v110, v111
	ds_read_b64 v[110:111], v101 offset:16384
	s_waitcnt lgkmcnt(0)
	v_mfma_f32_16x16x32_bf16 v[72:75], v[106:109], v[92:95], v[72:75]
	v_cvt_pk_bf16_f32 v84, v145, v147
	v_cvt_pk_bf16_f32 v85, v180, v181
	s_add_i32 s31, s31, 1
	v_mfma_f32_16x16x32_bf16 v[68:71], v[106:109], v[96:99], v[68:71]
	ds_read_b64 v[106:107], v101 offset:22528
	ds_read_b64 v[108:109], v114 offset:22528
	s_add_i32 s84, s84, 64
	s_add_i32 s30, s30, 0x8000
	v_mfma_f32_16x16x32_bf16 v[80:83], v[110:113], v[92:95], v[80:83]
	s_mov_b64 s[0:1], 0x4000
	v_lshl_add_u64 v[126:127], v[126:127], 0, s[70:71]
	v_lshl_add_u64 v[128:129], v[128:129], 0, s[0:1]
	v_mfma_f32_16x16x32_bf16 v[76:79], v[110:113], v[96:99], v[76:79]
	ds_read_b64 v[110:111], v101 offset:20480
	ds_read_b64 v[112:113], v114 offset:20480
	s_waitcnt lgkmcnt(0)
	v_mfma_f32_16x16x32_bf16 v[56:59], v[106:109], v[92:95], v[56:59]
	s_cmp_lg_u32 s31, 20
	v_mfma_f32_16x16x32_bf16 v[52:55], v[106:109], v[96:99], v[52:55]
	ds_read_b64 v[106:107], v101 offset:26624
	ds_read_b64 v[108:109], v114 offset:26624
	v_mfma_f32_16x16x32_bf16 v[64:67], v[110:113], v[92:95], v[64:67]
	v_mfma_f32_16x16x32_bf16 v[60:63], v[110:113], v[96:99], v[60:63]
	ds_read_b64 v[110:111], v101 offset:24576
	ds_read_b64 v[112:113], v114 offset:24576
	s_waitcnt lgkmcnt(0)
	v_mfma_f32_16x16x32_bf16 v[40:43], v[106:109], v[92:95], v[40:43]
	v_mfma_f32_16x16x32_bf16 v[36:39], v[106:109], v[96:99], v[36:39]
	ds_read_b64 v[106:107], v101 offset:30720
	ds_read_b64 v[108:109], v114 offset:30720
	v_add_u32_e32 v226, v0, v176
	v_mfma_f32_16x16x32_bf16 v[48:51], v[110:113], v[92:95], v[48:51]
	v_add_u32_e32 v228, v0, v177
	v_mfma_f32_16x16x32_bf16 v[44:47], v[110:113], v[96:99], v[44:47]
	ds_read_b64 v[110:111], v101 offset:28672
	ds_read_b64 v[112:113], v114 offset:28672
	s_waitcnt lgkmcnt(0)
	v_mfma_f32_16x16x32_bf16 v[32:35], v[110:113], v[92:95], v[32:35]
	v_mfma_f32_16x16x32_bf16 v[20:23], v[110:113], v[96:99], v[20:23]
	v_mfma_f32_16x16x32_bf16 v[24:27], v[106:109], v[92:95], v[24:27]
	ds_read_b64 v[102:103], v226 offset:16384
	s_waitcnt lgkmcnt(0)
	v_mfma_f32_16x16x32_bf16 v[28:31], v[106:109], v[96:99], v[28:31]
	ds_read_b64 v[96:97], v226 offset:18432
	ds_read_b64 v[104:105], v228 offset:16384
	ds_read_b64 v[98:99], v228 offset:18432
	s_waitcnt lgkmcnt(0)
	v_mfma_f32_16x16x32_bf16 v[80:83], v[102:105], v[84:87], v[80:83]
	s_nop 0
	v_mfma_f32_16x16x32_bf16 v[72:75], v[96:99], v[84:87], v[72:75]
	v_mfma_f32_16x16x32_bf16 v[68:71], v[96:99], v[88:91], v[68:71]
	ds_read_b64 v[96:97], v226 offset:22528
	ds_read_b64 v[98:99], v228 offset:22528
	v_mfma_f32_16x16x32_bf16 v[76:79], v[102:105], v[88:91], v[76:79]
	ds_read_b64 v[102:103], v226 offset:20480
	ds_read_b64 v[104:105], v228 offset:20480
	s_waitcnt lgkmcnt(0)
	s_nop 0
	v_mfma_f32_16x16x32_bf16 v[56:59], v[96:99], v[84:87], v[56:59]
	v_mfma_f32_16x16x32_bf16 v[52:55], v[96:99], v[88:91], v[52:55]
	ds_read_b64 v[96:97], v226 offset:26624
	ds_read_b64 v[98:99], v228 offset:26624
	v_mfma_f32_16x16x32_bf16 v[64:67], v[102:105], v[84:87], v[64:67]
	v_mfma_f32_16x16x32_bf16 v[60:63], v[102:105], v[88:91], v[60:63]
	ds_read_b64 v[102:103], v226 offset:24576
	ds_read_b64 v[104:105], v228 offset:24576
	s_waitcnt lgkmcnt(0)
	v_mfma_f32_16x16x32_bf16 v[40:43], v[96:99], v[84:87], v[40:43]
	v_mfma_f32_16x16x32_bf16 v[36:39], v[96:99], v[88:91], v[36:39]
	ds_read_b64 v[96:97], v226 offset:30720
	ds_read_b64 v[98:99], v228 offset:30720
	v_mfma_f32_16x16x32_bf16 v[48:51], v[102:105], v[84:87], v[48:51]
	v_mfma_f32_16x16x32_bf16 v[44:47], v[102:105], v[88:91], v[44:47]
	ds_read_b64 v[102:103], v226 offset:28672
	ds_read_b64 v[104:105], v228 offset:28672
	s_waitcnt lgkmcnt(0)
	v_mfma_f32_16x16x32_bf16 v[32:35], v[102:105], v[84:87], v[32:35]
	v_mfma_f32_16x16x32_bf16 v[20:23], v[102:105], v[88:91], v[20:23]
	v_mfma_f32_16x16x32_bf16 v[24:27], v[96:99], v[84:87], v[24:27]
	v_mfma_f32_16x16x32_bf16 v[28:31], v[96:99], v[88:91], v[28:31]
	s_cbranch_scc0 .LBB0_482
	v_mov_b32_e32 v178, v2
	v_mov_b32_e32 v179, v100
	v_mov_b32_e32 v100, v3
	v_mov_b32_e32 v181, v133
	s_branch .LBB0_614
